# v23: v22 + P12 sample-row conv strips moved to otherwise idle threads (WGs 176-219)
# baseline (speedup 1.0000x reference)
; __device__ __forceinline__ u32x4 pack8(const float* f) { u32x4 o; o.x = pk2(f[0], f[1]); o.y = pk2(f[2], f[3]); o.z = pk2(f[4], f[5]); o.w = pk2(f[6], f[7]); return o; }
; __global__ void __launch_bounds__(512, 2) mega_fwd(Args args) {
;     ...
;         for (int idx = gt; idx < 32 * NCH; idx += NGT) {
;             const int b = idx / NCH, ch = idx % NCH, c0 = ch * 8;
;             float cw0[8], cw1[8], cw2[8], cbv[8], g2[8], g1[8];
;             const float* sp = state_conv + ((size_t)b * 2) * FF + c0;
; #pragma unroll
;             for (int e = 0; e < 8; ++e) { cw0[e] = conv_w[c0 + e]; cw1[e] = conv_w[FF + c0 + e]; cw2[e] = conv_w[2 * FF + c0 + e]; cbv[e] = conv_b[c0 + e]; g2[e] = sp[e]; g1[e] = sp[FF + e]; }
;             for (int i = 0; i < 4; ++i) { const int row = T + b * 4 + i; float gc[8], uu[8], a[8];
;                 unpack8(*(const u32x4*)(GB + (size_t)row * FF + c0), gc); unpack8(*(const u32x4*)(UPB + (size_t)row * FF + c0), uu);
; #pragma unroll
;                 for (int e = 0; e < 8; ++e) { const float c = cbv[e] + cw0[e] * g2[e] + cw1[e] * g1[e] + cw2[e] * gc[e]; a[e] = c / (1.f + __expf(-c)) * uu[e]; g2[e] = g1[e]; g1[e] = gc[e]; }
;                 *(u32x4*)(UPB + (size_t)row * FF + c0) = pack8(a); }
;         }
.LBB0_836:
	s_or_b64 exec, exec, s[10:11]
	s_movk_i32 s4, 0x5800
	v_add_u32_e32 v50, 0xfffea000, v194
	v_cmp_gt_u32_e32 vcc, s4, v50
	s_and_saveexec_b64 s[30:31], vcc
	s_cbranch_execz .LBB0_841
	s_load_dwordx2 s[44:45], s[28:29], 0x38
	s_load_dwordx4 s[20:23], s[28:29], 0xd8
	s_load_dwordx2 s[46:47], s[28:29], 0xf8
	s_mov_b64 s[48:49], 0
	s_mov_b32 s27, 0x2e8ba2e9
	s_mov_b32 s33, 0xb000
	s_mov_b64 s[50:51], 0x5800
	s_mov_b64 s[52:53], 0xb000
	s_movk_i32 s34, 0x5000
	s_movk_i32 s35, 0x2c00
	s_brev_b32 s41, 52
	s_movk_i32 s56, 0x57ff
